# SSD diagonal pass item prologue: 12 B/x tile loads issued together into distinct registers, LDS writes behind counted vmcnt (was 12 serial load->vmcnt(0)->ds_write round trips per item); on top of v34
# speedup vs baseline: 1.0127x; 1.0127x over previous
; __device__ __forceinline__ void ssd_diag_item(CParams& p, int j2, int row0, int h, bf16_t* smem) {
;     ...
;     const float af = -expf(p.ssm_a_log[(j2 * 2 + 0) * 32 + h]);
;     const float ab = -expf(p.ssm_a_log[(j2 * 2 + 1) * 32 + h]);
;     const float dsk = p.ssm_d[j2 * 32 + h];
;     lds_sync();
; #pragma unroll
;     for (int i = 0; i < 8; ++i) {
;         const int c = tid + i * 256, r = c >> 4, kc = (c & 15) * 8;
;         *(u32x4*)(sB + r * SST + kc) = *(const u32x4*)(Bn + (size_t)(row0 + r) * 512 + kc);
;     }
; #pragma unroll
;     for (int i = 0; i < 4; ++i) {
;         const int c = tid + i * 256, r = c >> 4, kc = (c & 15) * 8;
;         *(u32x4*)(sX + r * SST + kc) = *(const u32x4*)(XT + (size_t)r * MT + row0 + kc);
;     }
;     {
;         const int d = wave >> 1;
;         const float d0 = DT[(size_t)(row0 + lane) * 64 + d * 32 + h], d1 = DT[(size_t)(row0 + 64 + lane) * 64 + d * 32 + h];
;         const float aa = d ? ab : af;
;         const f32x2 sc2 = scan128(d0 * aa, d1 * aa, lane, d);
.LBB0_425:
	s_lshl_b32 s8, s22, 2
	s_bfe_u32 s24, s22, 0x20003
	s_and_b32 s23, s22, 31
	s_and_b32 s8, s8, 0xffffff80
	s_lshl_b32 s9, s24, 8
	s_add_u32 s12, s16, s9
	s_addc_u32 s13, s17, 0
	s_or_b32 s78, s23, s18
	s_waitcnt vmcnt(27)
	v_mov_b32_e32 v1, v167
	s_lshl_b64 s[26:27], s[78:79], 2
	s_add_u32 s26, s52, s26
	v_lshlrev_b32_e32 v2, 4, v1
	s_waitcnt vmcnt(20)
	v_ashrrev_i32_e32 v21, 4, v1
	s_addc_u32 s27, s53, s27
	s_or_b32 s78, s23, s19
	v_and_b32_e32 v164, 0xf0, v2
	v_add_u32_e32 v2, s8, v21
	global_load_dword v9, v165, s[26:27]
	global_load_dword v20, v165, s[26:27] offset:128
	s_lshl_b64 s[26:27], s[78:79], 2
	v_ashrrev_i32_e32 v3, 31, v2
	s_add_u32 s26, s54, s26
	v_lshl_add_u64 v[6:7], s[12:13], 0, v[164:165]
	v_lshlrev_b64 v[2:3], 10, v[2:3]
	s_addc_u32 s27, s55, s27
	v_lshl_add_u64 v[2:3], v[6:7], 0, v[2:3]
	global_load_dword v96, v165, s[26:27]
	s_waitcnt vmcnt(63) expcnt(7) lgkmcnt(15)
	s_barrier
	global_load_dwordx4 v[140:143], v[2:3], off
	v_add_u32_e32 v8, 0, v164
	s_mov_b32 s27, 0x3fb8aa3b
	s_mul_i32 s9, s23, 0x210000
	s_add_u32 s25, s14, s9
	s_addc_u32 s26, s15, 0
	s_ashr_i32 s9, s8, 31
	s_mov_b32 s39, 0xc2ce8ed0
	s_mov_b32 s2, 0x42b17218
	v_and_b32_e32 v0, 63, v1
	s_mov_b32 s28, 0x3fb8aa3b
	s_mov_b32 s90, 0xc2ce8ed0
	s_mov_b32 s89, 0x42b17218
	s_waitcnt vmcnt(3)
	v_mad_u64_u32 v[10:11], s[12:13], v21, s91, v[8:9]
	v_cmp_ngt_f32_e32 vcc, s39, v9
	v_add_u32_e32 v2, 0x100, v1
	v_ashrrev_i32_e32 v11, 4, v2
	v_add_u32_e32 v2, s8, v11
	v_ashrrev_i32_e32 v3, 31, v2
	v_lshlrev_b64 v[2:3], 10, v[2:3]
	v_lshl_add_u64 v[2:3], v[6:7], 0, v[2:3]
	global_load_dwordx4 v[144:147], v[2:3], off
	v_mad_u64_u32 v[12:13], s[12:13], v11, s91, v[8:9]
	v_add_u32_e32 v2, 0x200, v1
	v_ashrrev_i32_e32 v13, 4, v2
	v_add_u32_e32 v2, s8, v13
	v_ashrrev_i32_e32 v3, 31, v2
	v_lshlrev_b64 v[2:3], 10, v[2:3]
	v_lshl_add_u64 v[2:3], v[6:7], 0, v[2:3]
	global_load_dwordx4 v[148:151], v[2:3], off
	v_mad_u64_u32 v[14:15], s[12:13], v13, s91, v[8:9]
	v_add_u32_e32 v2, 0x300, v1
	v_ashrrev_i32_e32 v15, 4, v2
	v_add_u32_e32 v2, s8, v15
	v_ashrrev_i32_e32 v3, 31, v2
	v_lshlrev_b64 v[2:3], 10, v[2:3]
	v_lshl_add_u64 v[2:3], v[6:7], 0, v[2:3]
	global_load_dwordx4 v[152:155], v[2:3], off
	v_mad_u64_u32 v[16:17], s[12:13], v15, s91, v[8:9]
	v_add_u32_e32 v2, 0x400, v1
	v_ashrrev_i32_e32 v17, 4, v2
	v_add_u32_e32 v2, s8, v17
	v_ashrrev_i32_e32 v3, 31, v2
	v_lshlrev_b64 v[2:3], 10, v[2:3]
	v_lshl_add_u64 v[2:3], v[6:7], 0, v[2:3]
	global_load_dwordx4 v[156:159], v[2:3], off
	v_mad_u64_u32 v[224:225], s[12:13], v17, s91, v[8:9]
	v_add_u32_e32 v2, 0x500, v1
	v_ashrrev_i32_e32 v17, 4, v2
	v_add_u32_e32 v2, s8, v17
	v_ashrrev_i32_e32 v3, 31, v2
	v_lshlrev_b64 v[2:3], 10, v[2:3]
	v_lshl_add_u64 v[2:3], v[6:7], 0, v[2:3]
	global_load_dwordx4 v[160:163], v[2:3], off
	v_mad_u64_u32 v[226:227], s[12:13], v17, s91, v[8:9]
	v_add_u32_e32 v2, 0x600, v1
	v_ashrrev_i32_e32 v17, 4, v2
	v_add_u32_e32 v2, s8, v17
	v_ashrrev_i32_e32 v3, 31, v2
	v_lshlrev_b64 v[2:3], 10, v[2:3]
	v_lshl_add_u64 v[2:3], v[6:7], 0, v[2:3]
	global_load_dwordx4 v[172:175], v[2:3], off
	v_mad_u64_u32 v[228:229], s[12:13], v17, s91, v[8:9]
	v_add_u32_e32 v2, 0x700, v1
	v_ashrrev_i32_e32 v17, 4, v2
	v_add_u32_e32 v2, s8, v17
	v_ashrrev_i32_e32 v3, 31, v2
	v_lshlrev_b64 v[2:3], 10, v[2:3]
	v_lshl_add_u64 v[2:3], v[6:7], 0, v[2:3]
	global_load_dwordx4 v[176:179], v[2:3], off
	v_mad_u64_u32 v[230:231], s[12:13], v17, s91, v[8:9]
	s_lshl_b64 s[12:13], s[8:9], 1
	s_add_u32 s12, s25, s12
	s_addc_u32 s13, s26, s13
	s_lshl_b32 s78, s23, 2
	s_movk_i32 s9, 0x7f
	v_cmp_lt_u32_e64 s[42:43], s9, v1
	s_movk_i32 s9, 0x80
	v_mul_f32_e32 v2, 0x3fb8aa3b, v9
	v_fma_f32 v3, v9, s27, -v2
	v_rndne_f32_e32 v4, v2
	v_fmac_f32_e32 v3, 0x32a5705f, v9
	v_sub_f32_e32 v2, v2, v4
	v_add_f32_e32 v2, v2, v3
	v_exp_f32_e32 v2, v2
	v_cvt_i32_f32_e32 v3, v4
	v_lshl_add_u64 v[6:7], s[12:13], 0, v[164:165]
	v_ldexp_f32 v2, v2, v3
	v_cndmask_b32_e32 v2, 0, v2, vcc
	v_cmp_nlt_f32_e32 vcc, s2, v9
	s_nop 1
	v_cndmask_b32_e32 v17, v208, v2, vcc
	v_mad_i64_i32 v[2:3], s[12:13], v21, s40, v[6:7]
	global_load_dwordx4 v[180:183], v[2:3], off
	v_mad_i64_i32 v[2:3], s[12:13], v11, s40, v[6:7]
	global_load_dwordx4 v[184:187], v[2:3], off
	v_mad_i64_i32 v[2:3], s[12:13], v13, s40, v[6:7]
	global_load_dwordx4 v[188:191], v[2:3], off
	v_mad_i64_i32 v[2:3], s[12:13], v15, s40, v[6:7]
	global_load_dwordx4 v[220:223], v[2:3], off
	s_waitcnt vmcnt(11)
	ds_write_b128 v10, v[140:143]
	s_waitcnt vmcnt(10)
	ds_write_b128 v12, v[144:147]
	s_waitcnt vmcnt(9)
	ds_write_b128 v14, v[148:151]
	s_waitcnt vmcnt(8)
	ds_write_b128 v16, v[152:155]
	s_waitcnt vmcnt(7)
	ds_write_b128 v224, v[156:159]
	s_waitcnt vmcnt(6)
	ds_write_b128 v226, v[160:163]
	s_waitcnt vmcnt(5)
	ds_write_b128 v228, v[172:175]
	s_waitcnt vmcnt(4)
	ds_write_b128 v230, v[176:179]
	s_waitcnt vmcnt(3)
	ds_write_b128 v10, v[180:183] offset:34816
	s_waitcnt vmcnt(2)
	ds_write_b128 v12, v[184:187] offset:34816
	s_waitcnt vmcnt(1)
	ds_write_b128 v14, v[188:191] offset:34816
	s_waitcnt vmcnt(0)
	ds_write_b128 v16, v[220:223] offset:34816
	v_cmp_ngt_f32_e32 vcc, s39, v20
	v_mul_f32_e32 v2, 0x3fb8aa3b, v20
	v_fma_f32 v3, v20, s27, -v2
	v_rndne_f32_e32 v4, v2
	v_fmac_f32_e32 v3, 0x32a5705f, v20
	v_sub_f32_e32 v2, v2, v4
	v_add_f32_e32 v2, v2, v3
	v_exp_f32_e32 v2, v2
	v_cvt_i32_f32_e32 v3, v4
	v_or_b32_e32 v4, s8, v0
	v_ashrrev_i32_e32 v5, 31, v4
	v_lshlrev_b64 v[6:7], 8, v[4:5]
	v_ldexp_f32 v2, v2, v3
	v_cndmask_b32_e32 v2, 0, v2, vcc
	v_cmp_nlt_f32_e32 vcc, s2, v20
	v_or_b32_e32 v4, 64, v4
	v_ashrrev_i32_e32 v5, 31, v4
	v_cndmask_b32_e32 v10, v208, v2, vcc
	v_ashrrev_i32_e32 v2, 2, v1
	v_and_b32_e32 v2, 0xffffffe0, v2
	v_ashrrev_i32_e32 v3, 31, v2
	v_lshlrev_b64 v[4:5], 8, v[4:5]
	v_lshl_add_u64 v[6:7], s[4:5], 0, v[6:7]
	v_lshlrev_b64 v[8:9], 2, v[2:3]
	v_lshl_add_u64 v[4:5], s[4:5], 0, v[4:5]
	v_lshl_add_u64 v[2:3], v[6:7], 0, v[8:9]
	v_lshl_add_u64 v[4:5], v[4:5], 0, v[8:9]
	v_lshl_add_u64 v[2:3], v[2:3], 0, s[78:79]
	v_lshl_add_u64 v[4:5], v[4:5], 0, s[78:79]
	global_load_dword v2, v[2:3], off
	v_cmp_gt_u32_e32 vcc, s9, v1
	global_load_dword v3, v[4:5], off
	s_nop 0
	v_cndmask_b32_e32 v4, v10, v17, vcc
	s_waitcnt vmcnt(1)
	v_mul_f32_e64 v7, v2, -v4
	s_waitcnt vmcnt(0)
	v_mul_f32_e64 v6, v3, -v4
	s_and_saveexec_b64 s[12:13], s[42:43]
	s_xor_b64 s[12:13], exec, s[12:13]
	s_cbranch_execz .LBB0_427
; __device__ __forceinline__ f32x2 scan128(float s0, float s1, int lane, int dir) {
;     ...
; #pragma unroll
;         for (int o = 1; o < 64; o <<= 1) { const float t0 = __shfl_down(s0, o), t1 = __shfl_down(s1, o); s0 += lane + o < 64 ? t0 : 0.f; s1 += lane + o < 64 ? t1 : 0.f; }
;         s0 += __shfl(s1, 0);
;     }
	v_and_b32_e32 v4, 63, v197
	v_cmp_ne_u32_e64 s[42:43], 63, v4
	s_nop 1
	v_addc_co_u32_e64 v5, s[42:43], 0, v197, s[42:43]
	v_lshlrev_b32_e32 v5, 2, v5
	ds_bpermute_b32 v8, v5, v7
	ds_bpermute_b32 v5, v5, v6
	v_cmp_eq_u32_e64 s[42:43], 63, v0
	s_waitcnt lgkmcnt(1)
	s_nop 0
	v_cndmask_b32_e64 v8, v8, 0, s[42:43]
	s_waitcnt lgkmcnt(0)
	v_cndmask_b32_e64 v5, v5, 0, s[42:43]
	v_cmp_gt_u32_e64 s[42:43], 62, v4
	v_add_f32_e32 v5, v6, v5
	v_add_f32_e32 v7, v7, v8
	v_cndmask_b32_e64 v6, 0, 2, s[42:43]
	v_add_lshl_u32 v6, v6, v197, 2
	ds_bpermute_b32 v8, v6, v7
	ds_bpermute_b32 v6, v6, v5
	v_cmp_gt_u32_e64 s[42:43], 62, v0
	s_waitcnt lgkmcnt(1)
	s_nop 0
	v_cndmask_b32_e64 v8, 0, v8, s[42:43]
	s_waitcnt lgkmcnt(0)
	v_cndmask_b32_e64 v6, 0, v6, s[42:43]
	v_cmp_gt_u32_e64 s[42:43], 60, v4
	v_add_f32_e32 v5, v5, v6
	v_add_f32_e32 v7, v7, v8
	v_cndmask_b32_e64 v6, 0, 4, s[42:43]
	v_add_lshl_u32 v6, v6, v197, 2
	ds_bpermute_b32 v8, v6, v7
	ds_bpermute_b32 v6, v6, v5
	v_cmp_gt_u32_e64 s[42:43], 60, v0
	s_waitcnt lgkmcnt(1)
	s_nop 0
	v_cndmask_b32_e64 v8, 0, v8, s[42:43]
	s_waitcnt lgkmcnt(0)
	v_cndmask_b32_e64 v6, 0, v6, s[42:43]
	v_cmp_gt_u32_e64 s[42:43], 56, v4
	v_add_f32_e32 v5, v5, v6
	v_add_f32_e32 v7, v7, v8
	v_cndmask_b32_e64 v6, 0, 8, s[42:43]
	v_add_lshl_u32 v6, v6, v197, 2
	ds_bpermute_b32 v8, v6, v7
	ds_bpermute_b32 v6, v6, v5
	v_cmp_gt_u32_e64 s[42:43], 56, v0
	s_waitcnt lgkmcnt(1)
	s_nop 0
	v_cndmask_b32_e64 v8, 0, v8, s[42:43]
	s_waitcnt lgkmcnt(0)
	v_cndmask_b32_e64 v6, 0, v6, s[42:43]
	v_cmp_gt_u32_e64 s[42:43], 48, v4
	v_add_f32_e32 v7, v7, v8
	v_add_f32_e32 v5, v5, v6
	v_cndmask_b32_e64 v4, 0, 16, s[42:43]
	v_add_lshl_u32 v4, v4, v197, 2
	ds_bpermute_b32 v6, v4, v7
	ds_bpermute_b32 v4, v4, v5
	v_cmp_gt_u32_e64 s[42:43], 48, v0
	s_waitcnt lgkmcnt(1)
	s_nop 0
	v_cndmask_b32_e64 v6, 0, v6, s[42:43]
	v_add_f32_e32 v6, v7, v6
	s_waitcnt lgkmcnt(0)
	v_cndmask_b32_e64 v4, 0, v4, s[42:43]
	v_lshlrev_b32_e32 v7, 2, v197
	v_add_f32_e32 v4, v5, v4
	v_or_b32_e32 v5, 0x80, v7
	ds_bpermute_b32 v8, v5, v6
	ds_bpermute_b32 v5, v5, v4
	v_cmp_gt_u32_e64 s[42:43], 32, v0
	s_waitcnt lgkmcnt(1)
	s_nop 0
	v_cndmask_b32_e64 v8, 0, v8, s[42:43]
	s_waitcnt lgkmcnt(0)
	v_cndmask_b32_e64 v5, 0, v5, s[42:43]
	v_add_f32_e32 v5, v4, v5
	v_and_b32_e32 v4, 0x100, v7
	ds_bpermute_b32 v4, v4, v5
	v_add_f32_e32 v6, v6, v8
	s_waitcnt lgkmcnt(0)
	v_add_f32_e32 v4, v6, v4
